# non-temporal hint on the read-once adaLN weight stream (302 MB) in the P0 GEMV loop, on top of tail-fill conversion + nt
# speedup vs baseline: 1.0078x; 1.0005x over previous
.LBB0_30:
	v_lshl_add_u64 v[98:99], v[86:87], 0, s[12:13]
	v_add_co_u32_e32 v104, vcc, s20, v98
	s_mov_b32 s9, 0x24000
	s_nop 0
	v_addc_co_u32_e32 v105, vcc, 0, v99, vcc
	v_add_co_u32_e32 v106, vcc, s9, v98
	s_mov_b32 s9, 0x36000
	s_nop 0
	v_addc_co_u32_e32 v107, vcc, 0, v99, vcc
	v_add_co_u32_e32 v108, vcc, s9, v98
	s_mov_b32 s9, 0x48000
	s_nop 0
	v_addc_co_u32_e32 v109, vcc, 0, v99, vcc
	v_add_co_u32_e32 v110, vcc, s9, v98
	s_mov_b32 s9, 0x5a000
	s_nop 0
	v_addc_co_u32_e32 v111, vcc, 0, v99, vcc
	v_add_co_u32_e32 v112, vcc, s9, v98
	s_mov_b32 s9, 0x6c000
	s_nop 0
	v_addc_co_u32_e32 v113, vcc, 0, v99, vcc
	v_add_co_u32_e32 v114, vcc, s9, v98
	s_mov_b32 s9, 0x7e000
	s_nop 0
	v_addc_co_u32_e32 v115, vcc, 0, v99, vcc
	v_add_co_u32_e32 v116, vcc, s9, v98
	s_mov_b32 s9, 0x90000
	s_nop 0
	v_addc_co_u32_e32 v117, vcc, 0, v99, vcc
	v_add_co_u32_e32 v118, vcc, s9, v98
	ds_read_b128 v[14:17], v84
	ds_read_b128 v[10:13], v84 offset:16
	ds_read_b128 v[6:9], v84 offset:32
	ds_read_b128 v[2:5], v84 offset:48
	ds_read_b128 v[18:21], v84 offset:8192
	ds_read_b128 v[22:25], v84 offset:8208
	ds_read_b128 v[34:37], v84 offset:16384
	ds_read_b128 v[26:29], v84 offset:16400
	ds_read_b128 v[38:41], v84 offset:24576
	ds_read_b128 v[30:33], v84 offset:24592
	ds_read_b128 v[42:45], v84 offset:32768
	ds_read_b128 v[46:49], v84 offset:32784
	ds_read_b128 v[50:53], v84 offset:8224
	ds_read_b128 v[54:57], v84 offset:8240
	ds_read_b128 v[70:73], v84 offset:16416
	ds_read_b128 v[58:61], v84 offset:16432
	ds_read_b128 v[74:77], v84 offset:24608
	ds_read_b128 v[62:65], v84 offset:24624
	ds_read_b128 v[78:81], v84 offset:32800
	ds_read_b128 v[66:69], v84 offset:32816
	global_load_dwordx2 v[102:103], v[98:99], off nt
	v_addc_co_u32_e32 v119, vcc, 0, v99, vcc
	s_mov_b32 s9, 0xa2000
	v_add_co_u32_e32 v120, vcc, s9, v98
	s_mov_b32 s9, 0xb4000
	s_nop 0
	v_addc_co_u32_e32 v121, vcc, 0, v99, vcc
	v_add_co_u32_e32 v122, vcc, s9, v98
	s_mov_b32 s9, 0xc6000
	s_nop 0
	v_addc_co_u32_e32 v123, vcc, 0, v99, vcc
	v_add_co_u32_e32 v124, vcc, s9, v98
	s_mov_b32 s9, 0xd8000
	s_nop 0
	v_addc_co_u32_e32 v125, vcc, 0, v99, vcc
	v_add_co_u32_e32 v126, vcc, s9, v98
	s_mov_b32 s9, 0xea000
	s_nop 0
	v_addc_co_u32_e32 v127, vcc, 0, v99, vcc
	v_add_co_u32_e32 v128, vcc, s9, v98
	global_load_dwordx2 v[104:105], v[104:105], off nt
	s_nop 0
	global_load_dwordx2 v[106:107], v[106:107], off nt
	s_nop 0
	global_load_dwordx2 v[108:109], v[108:109], off nt
	s_nop 0
	global_load_dwordx2 v[110:111], v[110:111], off nt
	s_nop 0
	global_load_dwordx2 v[112:113], v[112:113], off nt
	s_nop 0
	global_load_dwordx2 v[114:115], v[114:115], off nt
	s_nop 0
	global_load_dwordx2 v[116:117], v[116:117], off nt
	s_nop 0
	global_load_dwordx2 v[118:119], v[118:119], off nt
	s_nop 0
	global_load_dwordx2 v[120:121], v[120:121], off nt
	s_nop 0
	global_load_dwordx2 v[122:123], v[122:123], off nt
	v_addc_co_u32_e32 v129, vcc, 0, v99, vcc
	v_add_co_u32_e32 v130, vcc, s21, v98
	s_waitcnt lgkmcnt(14)
	v_mov_b32_e32 v132, v17
	v_addc_co_u32_e32 v131, vcc, 0, v99, vcc
	v_add_co_u32_e32 v98, vcc, s22, v98
	v_mov_b32_e32 v134, v21
	s_nop 0
	v_addc_co_u32_e32 v99, vcc, 0, v99, vcc
	global_load_dwordx2 v[124:125], v[124:125], off nt
	s_nop 0
	global_load_dwordx2 v[126:127], v[126:127], off nt
	s_nop 0
	global_load_dwordx2 v[128:129], v[128:129], off nt
	s_nop 0
	global_load_dwordx2 v[130:131], v[130:131], off nt
	s_nop 0
	global_load_dwordx2 v[98:99], v[98:99], off nt
	s_waitcnt lgkmcnt(13)
	v_mov_b32_e32 v136, v37
	s_waitcnt lgkmcnt(11)
	v_mov_b32_e32 v138, v41
	s_waitcnt lgkmcnt(9)
	v_mov_b32_e32 v140, v45
	v_mov_b32_e32 v142, v13
	v_mov_b32_e32 v144, v25
	v_mov_b32_e32 v146, v29
	v_mov_b32_e32 v148, v33
	s_waitcnt lgkmcnt(8)
	v_mov_b32_e32 v150, v49
	v_mov_b32_e32 v152, v9
	s_waitcnt lgkmcnt(7)
	v_mov_b32_e32 v154, v53
	s_waitcnt lgkmcnt(5)
	v_mov_b32_e32 v156, v73
	s_waitcnt lgkmcnt(3)
	v_mov_b32_e32 v158, v77
	s_waitcnt lgkmcnt(1)
	v_mov_b32_e32 v160, v81
	s_add_u32 s12, s12, 0x120000
	s_addc_u32 s13, s13, 0
	v_mov_b32_e32 v162, v5
	v_mov_b32_e32 v164, v57
	v_mov_b32_e32 v166, v61
	v_mov_b32_e32 v168, v65
	s_waitcnt lgkmcnt(0)
	v_mov_b32_e32 v170, v69
	v_add_u32_e32 v84, 64, v84
	s_cmp_eq_u32 s12, 0x900000
	s_waitcnt vmcnt(15)
	v_pk_fma_f32 v[90:91], v[102:103], v[14:15], v[90:91] op_sel_hi:[1,0,1]
	v_pk_fma_f32 v[92:93], v[102:103], v[18:19], v[92:93] op_sel_hi:[1,0,1]
	v_pk_fma_f32 v[94:95], v[102:103], v[34:35], v[94:95] op_sel_hi:[1,0,1]
	v_pk_fma_f32 v[96:97], v[102:103], v[38:39], v[96:97] op_sel_hi:[1,0,1]
	v_pk_fma_f32 v[88:89], v[102:103], v[42:43], v[88:89] op_sel_hi:[1,0,1]
	s_waitcnt vmcnt(14)
	v_pk_fma_f32 v[14:15], v[104:105], v[14:15], v[90:91] op_sel:[0,1,0]
	v_pk_fma_f32 v[18:19], v[104:105], v[18:19], v[92:93] op_sel:[0,1,0]
	v_pk_fma_f32 v[34:35], v[104:105], v[34:35], v[94:95] op_sel:[0,1,0]
	v_pk_fma_f32 v[38:39], v[104:105], v[38:39], v[96:97] op_sel:[0,1,0]
	v_pk_fma_f32 v[42:43], v[104:105], v[42:43], v[88:89] op_sel:[0,1,0]
	s_waitcnt vmcnt(13)
	v_pk_fma_f32 v[14:15], v[106:107], v[16:17], v[14:15] op_sel_hi:[1,0,1]
	v_pk_fma_f32 v[16:17], v[106:107], v[20:21], v[18:19] op_sel_hi:[1,0,1]
	v_pk_fma_f32 v[18:19], v[106:107], v[36:37], v[34:35] op_sel_hi:[1,0,1]
	v_pk_fma_f32 v[20:21], v[106:107], v[40:41], v[38:39] op_sel_hi:[1,0,1]
	v_pk_fma_f32 v[34:35], v[106:107], v[44:45], v[42:43] op_sel_hi:[1,0,1]
	s_waitcnt vmcnt(12)
	v_pk_fma_f32 v[14:15], v[108:109], v[132:133], v[14:15] op_sel_hi:[1,0,1]
	v_pk_fma_f32 v[16:17], v[108:109], v[134:135], v[16:17] op_sel_hi:[1,0,1]
	v_pk_fma_f32 v[18:19], v[108:109], v[136:137], v[18:19] op_sel_hi:[1,0,1]
	v_pk_fma_f32 v[20:21], v[108:109], v[138:139], v[20:21] op_sel_hi:[1,0,1]
	v_pk_fma_f32 v[34:35], v[108:109], v[140:141], v[34:35] op_sel_hi:[1,0,1]
	s_waitcnt vmcnt(11)
	v_pk_fma_f32 v[14:15], v[110:111], v[10:11], v[14:15] op_sel_hi:[1,0,1]
	v_pk_fma_f32 v[16:17], v[110:111], v[22:23], v[16:17] op_sel_hi:[1,0,1]
	v_pk_fma_f32 v[18:19], v[110:111], v[26:27], v[18:19] op_sel_hi:[1,0,1]
	v_pk_fma_f32 v[20:21], v[110:111], v[30:31], v[20:21] op_sel_hi:[1,0,1]
	v_pk_fma_f32 v[34:35], v[110:111], v[46:47], v[34:35] op_sel_hi:[1,0,1]
	s_waitcnt vmcnt(10)
	v_pk_fma_f32 v[10:11], v[112:113], v[10:11], v[14:15] op_sel:[0,1,0]
	v_pk_fma_f32 v[14:15], v[112:113], v[22:23], v[16:17] op_sel:[0,1,0]
	v_pk_fma_f32 v[16:17], v[112:113], v[26:27], v[18:19] op_sel:[0,1,0]
	v_pk_fma_f32 v[18:19], v[112:113], v[30:31], v[20:21] op_sel:[0,1,0]
	v_pk_fma_f32 v[20:21], v[112:113], v[46:47], v[34:35] op_sel:[0,1,0]
	s_waitcnt vmcnt(9)
	v_pk_fma_f32 v[10:11], v[114:115], v[12:13], v[10:11] op_sel_hi:[1,0,1]
	v_pk_fma_f32 v[12:13], v[114:115], v[24:25], v[14:15] op_sel_hi:[1,0,1]
	v_pk_fma_f32 v[14:15], v[114:115], v[28:29], v[16:17] op_sel_hi:[1,0,1]
	v_pk_fma_f32 v[16:17], v[114:115], v[32:33], v[18:19] op_sel_hi:[1,0,1]
	v_pk_fma_f32 v[18:19], v[114:115], v[48:49], v[20:21] op_sel_hi:[1,0,1]
	s_waitcnt vmcnt(8)
	v_pk_fma_f32 v[10:11], v[116:117], v[142:143], v[10:11] op_sel_hi:[1,0,1]
	v_pk_fma_f32 v[12:13], v[116:117], v[144:145], v[12:13] op_sel_hi:[1,0,1]
	v_pk_fma_f32 v[14:15], v[116:117], v[146:147], v[14:15] op_sel_hi:[1,0,1]
	v_pk_fma_f32 v[16:17], v[116:117], v[148:149], v[16:17] op_sel_hi:[1,0,1]
	v_pk_fma_f32 v[18:19], v[116:117], v[150:151], v[18:19] op_sel_hi:[1,0,1]
	s_waitcnt vmcnt(7)
	v_pk_fma_f32 v[10:11], v[118:119], v[6:7], v[10:11] op_sel_hi:[1,0,1]
	v_pk_fma_f32 v[12:13], v[118:119], v[50:51], v[12:13] op_sel_hi:[1,0,1]
	v_pk_fma_f32 v[14:15], v[118:119], v[70:71], v[14:15] op_sel_hi:[1,0,1]
	v_pk_fma_f32 v[16:17], v[118:119], v[74:75], v[16:17] op_sel_hi:[1,0,1]
	v_pk_fma_f32 v[18:19], v[118:119], v[78:79], v[18:19] op_sel_hi:[1,0,1]
	s_waitcnt vmcnt(6)
	v_pk_fma_f32 v[6:7], v[120:121], v[6:7], v[10:11] op_sel:[0,1,0]
	v_pk_fma_f32 v[10:11], v[120:121], v[50:51], v[12:13] op_sel:[0,1,0]
	v_pk_fma_f32 v[12:13], v[120:121], v[70:71], v[14:15] op_sel:[0,1,0]
	v_pk_fma_f32 v[14:15], v[120:121], v[74:75], v[16:17] op_sel:[0,1,0]
	v_pk_fma_f32 v[16:17], v[120:121], v[78:79], v[18:19] op_sel:[0,1,0]
	s_waitcnt vmcnt(5)
	v_pk_fma_f32 v[6:7], v[122:123], v[8:9], v[6:7] op_sel_hi:[1,0,1]
	v_pk_fma_f32 v[8:9], v[122:123], v[52:53], v[10:11] op_sel_hi:[1,0,1]
	v_pk_fma_f32 v[10:11], v[122:123], v[72:73], v[12:13] op_sel_hi:[1,0,1]
	v_pk_fma_f32 v[12:13], v[122:123], v[76:77], v[14:15] op_sel_hi:[1,0,1]
	v_pk_fma_f32 v[14:15], v[122:123], v[80:81], v[16:17] op_sel_hi:[1,0,1]
	s_waitcnt vmcnt(4)
	v_pk_fma_f32 v[6:7], v[124:125], v[152:153], v[6:7] op_sel_hi:[1,0,1]
	v_pk_fma_f32 v[8:9], v[124:125], v[154:155], v[8:9] op_sel_hi:[1,0,1]
	v_pk_fma_f32 v[10:11], v[124:125], v[156:157], v[10:11] op_sel_hi:[1,0,1]
	v_pk_fma_f32 v[12:13], v[124:125], v[158:159], v[12:13] op_sel_hi:[1,0,1]
	v_pk_fma_f32 v[14:15], v[124:125], v[160:161], v[14:15] op_sel_hi:[1,0,1]
	s_waitcnt vmcnt(3)
	v_pk_fma_f32 v[6:7], v[126:127], v[2:3], v[6:7] op_sel_hi:[1,0,1]
	v_pk_fma_f32 v[8:9], v[126:127], v[54:55], v[8:9] op_sel_hi:[1,0,1]
	v_pk_fma_f32 v[10:11], v[126:127], v[58:59], v[10:11] op_sel_hi:[1,0,1]
	v_pk_fma_f32 v[12:13], v[126:127], v[62:63], v[12:13] op_sel_hi:[1,0,1]
	v_pk_fma_f32 v[14:15], v[126:127], v[66:67], v[14:15] op_sel_hi:[1,0,1]
	s_waitcnt vmcnt(2)
	v_pk_fma_f32 v[2:3], v[128:129], v[2:3], v[6:7] op_sel:[0,1,0]
	v_pk_fma_f32 v[6:7], v[128:129], v[54:55], v[8:9] op_sel:[0,1,0]
	v_pk_fma_f32 v[8:9], v[128:129], v[58:59], v[10:11] op_sel:[0,1,0]
	v_pk_fma_f32 v[10:11], v[128:129], v[62:63], v[12:13] op_sel:[0,1,0]
	v_pk_fma_f32 v[12:13], v[128:129], v[66:67], v[14:15] op_sel:[0,1,0]
	s_waitcnt vmcnt(1)
	v_pk_fma_f32 v[2:3], v[130:131], v[4:5], v[2:3] op_sel_hi:[1,0,1]
	v_pk_fma_f32 v[4:5], v[130:131], v[56:57], v[6:7] op_sel_hi:[1,0,1]
	v_pk_fma_f32 v[6:7], v[130:131], v[60:61], v[8:9] op_sel_hi:[1,0,1]
	v_pk_fma_f32 v[8:9], v[130:131], v[64:65], v[10:11] op_sel_hi:[1,0,1]
	v_pk_fma_f32 v[10:11], v[130:131], v[68:69], v[12:13] op_sel_hi:[1,0,1]
	s_waitcnt vmcnt(0)
	v_pk_fma_f32 v[90:91], v[98:99], v[162:163], v[2:3] op_sel_hi:[1,0,1]
	v_pk_fma_f32 v[92:93], v[98:99], v[164:165], v[4:5] op_sel_hi:[1,0,1]
	v_pk_fma_f32 v[94:95], v[98:99], v[166:167], v[6:7] op_sel_hi:[1,0,1]
	v_pk_fma_f32 v[96:97], v[98:99], v[168:169], v[8:9] op_sel_hi:[1,0,1]
	v_pk_fma_f32 v[88:89], v[98:99], v[170:171], v[10:11] op_sel_hi:[1,0,1]
	s_cbranch_scc0 .LBB0_30
	ds_write2st64_b64 v101, v[90:91], v[92:93] offset0:80 offset1:81
	ds_write2st64_b64 v101, v[94:95], v[96:97] offset0:82 offset1:83
	ds_write_b64 v101, v[88:89] offset:43008
	s_waitcnt lgkmcnt(0)
	s_barrier
	s_and_saveexec_b64 s[12:13], s[0:1]
	s_cbranch_execz .LBB0_28
	s_add_u32 s10, s16, s10
	s_addc_u32 s11, s17, s11
	s_bitcmp0_b32 s34, 0
	s_mul_i32 s26, s35, 0x4800
	s_cselect_b64 s[14:15], -1, 0
	s_add_i32 s26, s26, s8
	s_mul_i32 s35, s35, 5
	s_mov_b64 s[8:9], 0
	v_mov_b32_e32 v2, v1
	s_branch .LBB0_34
